# LDS bank conflicts: GQA K tile swizzle extended with row bit 4 so each ds_read_b128 lane group covers all 16 bank slots (was 2-way conflicted)
# speedup vs baseline: 1.0022x; 1.0022x over previous
; __device__ __forceinline__ int v_st(int k, int c) { const int kk = (k & ~0xC) | ((k & 4) << 1) | ((k & 8) >> 1); return ((kk >> 3) * 4 + (c >> 5)) * 512 + ((kk & 7) * 32 + (c & 31)) * 2; }
; __device__ __forceinline__ int v_rd_base(int lane) { return ((lane & 3) << 3) | (((lane >> 2) & 3) << 6) | (((lane >> 4) & 1) << 5) | (((lane >> 5) & 1) << 8); }
; #define SLOAD(i, k0) do { sr_[i].vs0 = *(const bf16x8*)(&Vh[(long)((k0) + sr) * LDK + sc]); sr_[i].vs1 = *(const bf16x8*)(&Vh[(long)((k0) + 32 + sr) * LDK + sc]); \
;     sr_[i].ks0 = *(const bf16x8*)(&Kh[(long)((k0) + sr) * LDK + sc]); sr_[i].ks1 = *(const bf16x8*)(&Kh[(long)((k0) + 32 + sr) * LDK + sc]); } while (0)
; #define SWRITE(b, i) do { *(bf16x8*)(V_lds + (b) * SHM_V + vst0) = sr_[i].vs0;          \
;     *(bf16x8*)(V_lds + (b) * SHM_V + vst1) = sr_[i].vs1; int kc = sc * 2;               \
;     *(bf16x8*)(K_lds + (b) * SHM_K + KSWZ(sr, kc)) = sr_[i].ks0;                       \
;     *(bf16x8*)(K_lds + (b) * SHM_K + KSWZ(32 + sr, kc)) = sr_[i].ks1; } while (0)
; template <int MODE, int SDEPTH, bool SIMPLE>
; __device__ __forceinline__ void attn_body(const Unit& U, char* lds, const int tid) {
;     ...
;   const bf16_t* Qw = U.Q + (long)(wid * QBLK + r32) * U.ldq + hi * 8;
; #pragma unroll
;   for (int d0 = 0; d0 < 8; ++d0) qr[d0] = *reinterpret_cast<const bf16x8*>(Qw + d0 * 16);
;   const int sr = tid >> 4, sc = (tid & 15) * 8, vst0 = v_st(sr, sc), vst1 = v_st(32 + sr, sc);
;   const int vb0 = (int)(uintptr_t)V_lds + v_rd_base(lane);
;   const bf16_t* Kh = U.K; const bf16_t* Vh = U.V; const int LDK = U.ldk;
;   struct { bf16x8 vs0, vs1, ks0, ks1; } sr_[SDEPTH];
;     ...
;   SLOAD(SE, 0); asm volatile("s_waitcnt vmcnt(0)" ::: "memory"); SWRITE(0, SE); __syncthreads();
;   qkt(pA0, pA1, K_lds, qr, r32, hi); amask<MODE>(pA0, pA1, 0, U, wid, r32, hi, tbl); partialSM(pA0, pA1, m_reg, mnA, alA);
.LBB0_198:
	s_ashr_i32 s30, s0, 8
	s_lshl_b32 s1, s0, 5
	s_and_b32 s16, s0, 7
	s_and_b32 s19, s1, 0x1f00
	s_lshl_b32 s1, s30, 3
	s_or_b32 s2, s1, s16
	s_ashr_i32 s3, s2, 31
	s_bfe_u32 s15, s28, 0x10002
	s_lshl_b64 s[2:3], s[2:3], 21
	s_add_u32 s1, s17, s2
	s_addc_u32 s2, s25, s3
	s_lshl_b32 s3, s19, 8
	s_add_u32 s36, s1, s3
	s_addc_u32 s37, s2, 0
	s_lshl_b32 s21, s30, 1
	s_bfe_u32 s0, s0, 0x10002
	s_or_b32 s0, s21, s0
	s_ashr_i32 s1, s0, 31
	s_waitcnt vmcnt(0)
	v_mov_b32_e32 v52, v177
	s_barrier
	s_lshl_b64 s[2:3], s[0:1], 21
	s_add_u32 s0, s58, s2
	v_ashrrev_i32_e32 v16, 4, v52
	v_lshlrev_b32_e32 v22, 3, v52
	v_add_u32_e32 v18, 32, v16
	s_addc_u32 s1, s59, s3
	v_and_b32_e32 v176, 0x78, v22
	v_ashrrev_i32_e32 v17, 31, v16
	v_ashrrev_i32_e32 v19, 31, v18
	s_add_u32 s2, s60, s2
	v_lshlrev_b32_e32 v23, 1, v176
	v_lshlrev_b64 v[48:49], 8, v[16:17]
	v_lshlrev_b64 v[12:13], 8, v[18:19]
	s_addc_u32 s3, s61, s3
	v_or_b32_e32 v50, v48, v23
	v_mov_b32_e32 v51, v49
	v_or_b32_e32 v12, v12, v23
	v_lshl_add_u64 v[0:1], s[2:3], 0, v[50:51]
	v_lshl_add_u64 v[4:5], s[2:3], 0, v[12:13]
	global_load_dwordx4 v[0:3], v[0:1], off
	s_nop 0
	global_load_dwordx4 v[4:7], v[4:5], off
	v_lshl_add_u64 v[8:9], s[0:1], 0, v[50:51]
	v_ashrrev_i32_e32 v184, 6, v52
	global_load_dwordx4 v[8:11], v[8:9], off
	v_lshl_add_u64 v[12:13], s[0:1], 0, v[12:13]
	v_and_b32_e32 v183, 31, v52
	v_lshlrev_b32_e32 v180, 5, v184
	global_load_dwordx4 v[12:15], v[12:13], off
	v_or_b32_e32 v20, v180, v183
	v_ashrrev_i32_e32 v21, 31, v20
	v_bfe_u32 v182, v52, 5, 1
	v_lshlrev_b64 v[20:21], 8, v[20:21]
	v_lshl_add_u64 v[20:21], s[36:37], 0, v[20:21]
	v_lshlrev_b32_e32 v192, 4, v182
	v_lshl_add_u64 v[20:21], v[20:21], 0, v[192:193]
	global_load_dwordx4 v[116:119], v[20:21], off
	global_load_dwordx4 v[112:115], v[20:21], off offset:32
	global_load_dwordx4 v[124:127], v[20:21], off offset:64
	global_load_dwordx4 v[120:123], v[20:21], off offset:96
	global_load_dwordx4 v[108:111], v[20:21], off offset:128
	global_load_dwordx4 v[104:107], v[20:21], off offset:160
	global_load_dwordx4 v[100:103], v[20:21], off offset:192
	global_load_dwordx4 v[96:99], v[20:21], off offset:224
	v_and_b32_e32 v19, 0xfffff0, v16
	v_lshlrev_b32_e32 v24, 1, v16
	v_lshrrev_b32_e32 v25, 1, v16
	v_and_b32_e32 v26, 3, v16
	v_and_or_b32 v19, v24, 8, v19
	v_and_or_b32 v24, v25, 4, v26
	v_and_b32_e32 v25, 0xfffff0, v18
	v_lshlrev_b32_e32 v26, 1, v18
	v_and_b32_e32 v17, 0x70, v52
	v_lshrrev_b32_e32 v211, 1, v52
	v_and_b32_e32 v211, 0x80, v211
	v_or_b32_e32 v17, v17, v211
	v_bfe_u32 v22, v22, 5, 2
	v_lshlrev_b32_e32 v16, 8, v16
	v_lshrrev_b32_e32 v19, 1, v19
	v_and_or_b32 v25, v26, 8, v25
	v_bitop3_b32 v16, v23, v16, v17 bitop3:0xde
	v_or_b32_e32 v19, v19, v22
	v_lshrrev_b32_e32 v25, 1, v25
	v_lshlrev_b32_e32 v24, 6, v24
	v_and_b32_e32 v27, 48, v23
	v_add_u32_e32 v190, 0, v16
	v_lshlrev_b32_e32 v16, 9, v19
	v_or_b32_e32 v19, v25, v22
	v_or3_b32 v16, v16, v24, v27
	v_lshlrev_b32_e32 v19, 9, v19
	v_lshlrev_b32_e32 v53, 4, v52
	v_lshlrev_b32_e32 v18, 8, v18
	v_or3_b32 v19, v19, v24, v27
	v_add_u32_e32 v191, 0, v16
	v_add_u32_e32 v202, 0, v19
	s_waitcnt vmcnt(0)
	v_and_b32_e32 v181, 63, v52
	s_add_i32 s22, 0, 0x11800
	s_mov_b64 s[26:27], 0x4000
	s_mov_b32 s41, s40
	v_lshl_add_u64 v[62:63], v[50:51], 0, s[26:27]
	s_mov_b64 s[26:27], 0x6000
	s_mov_b32 s42, s40
	s_mov_b32 s43, s40
	s_waitcnt vmcnt(11)
	ds_write_b128 v191, v[0:3]
	s_waitcnt vmcnt(10)
	ds_write_b128 v202, v[4:7]
	s_waitcnt vmcnt(9)
	ds_write_b128 v190, v[8:11] offset:32768
	v_bitop3_b32 v0, v23, v18, v17 bitop3:0xde
	v_lshlrev_b32_e32 v8, 8, v183
	v_and_b32_e32 v9, 0x70, v53
	v_lshlrev_b32_e32 v211, 3, v183
	v_and_b32_e32 v211, 0x80, v211
	v_or_b32_e32 v9, v9, v211
	v_add_u32_e32 v203, 0, v0
	v_bitop3_b32 v0, v192, v8, v9 bitop3:0xde
	v_add_u32_e32 v204, 0, v0
	s_waitcnt vmcnt(8)
	ds_write_b128 v203, v[12:15] offset:32768
	s_waitcnt lgkmcnt(0)
	s_barrier
	ds_read_b128 v[0:3], v204 offset:32768
	ds_read_b128 v[4:7], v204 offset:40960
	s_waitcnt vmcnt(7) lgkmcnt(1)
	v_mfma_f32_32x32x16_bf16 v[32:47], v[0:3], v[116:119], 0
	v_or_b32_e32 v0, 32, v192
	v_bitop3_b32 v0, v0, v8, v9 bitop3:0xde
	v_add_u32_e32 v211, 0, v0
	v_lshlrev_b32_e32 v10, 3, v181
	v_lshlrev_b32_e32 v12, 1, v52
	s_mov_b32 s44, s40
	s_mov_b32 s45, s40
	s_waitcnt lgkmcnt(0)
	v_mfma_f32_32x32x16_bf16 v[16:31], v[4:7], v[116:119], 0
	ds_read_b128 v[0:3], v211 offset:32768
	ds_read_b128 v[4:7], v211 offset:40960
	s_mov_b32 s46, s40
	s_mov_b32 s47, s40
	s_mov_b32 s48, s40
	s_mov_b32 s49, s40
	s_mov_b32 s50, s40
	s_mov_b32 s51, s40
	s_waitcnt vmcnt(6) lgkmcnt(1)
	v_mfma_f32_32x32x16_bf16 v[32:47], v[0:3], v[112:115], v[32:47]
	v_or_b32_e32 v0, 64, v192
	v_bitop3_b32 v0, v0, v8, v9 bitop3:0xde
	v_add_u32_e32 v210, 0, v0
	s_mov_b32 s52, s40
	s_mov_b32 s53, s40
	s_mov_b32 s54, s40
	s_mov_b32 s55, s40
	s_waitcnt lgkmcnt(0)
	v_mfma_f32_32x32x16_bf16 v[16:31], v[4:7], v[112:115], v[16:31]
	ds_read_b128 v[0:3], v210 offset:32768
	ds_read_b128 v[4:7], v210 offset:40960
	v_lshl_add_u64 v[64:65], v[50:51], 0, s[26:27]
	v_lshl_add_u64 v[58:59], s[2:3], 0, v[64:65]
	v_lshl_add_u64 v[66:67], s[0:1], 0, v[64:65]
	s_mov_b64 s[26:27], 0xa000
	s_cmp_lg_u32 0, -1
	s_mov_b32 s20, 1
	s_waitcnt vmcnt(5) lgkmcnt(1)
	v_mfma_f32_32x32x16_bf16 v[32:47], v[0:3], v[124:127], v[32:47]
	v_or_b32_e32 v0, 0x60, v192
	v_bitop3_b32 v0, v0, v8, v9 bitop3:0xde
	v_add_u32_e32 v208, 0, v0
	v_cmp_gt_u32_e64 s[36:37], 32, v181
	v_mov_b32_e32 v187, 0
	s_waitcnt lgkmcnt(0)
	v_mfma_f32_32x32x16_bf16 v[16:31], v[4:7], v[124:127], v[16:31]
	ds_read_b128 v[0:3], v208 offset:32768
	ds_read_b128 v[4:7], v208 offset:40960
	s_waitcnt vmcnt(4) lgkmcnt(1)
; __device__ __forceinline__ int v_rd_base(int lane) { return ((lane & 3) << 3) | (((lane >> 2) & 3) << 6) | (((lane >> 4) & 1) << 5) | (((lane >> 5) & 1) << 8); }
; __device__ __forceinline__ void qkt(f32x16& p0, f32x16& p1, const char* Ks, const bf16x8* qr, int r32, int hi) {
;   p0 = f32x16{}; p1 = f32x16{};
; #pragma unroll
;   for (int d0 = 0; d0 < 8; ++d0) { int cb = (d0 * 16 + hi * 8) * 2;
;     bf16x8 b0 = *reinterpret_cast<const bf16x8*>(Ks + KSWZ(r32, cb));
;     bf16x8 b1 = *reinterpret_cast<const bf16x8*>(Ks + KSWZ(32 + r32, cb));
;     p0 = __builtin_amdgcn_mfma_f32_32x32x16_bf16(b0, qr[d0], p0, 0, 0, 0);
;     p1 = __builtin_amdgcn_mfma_f32_32x32x16_bf16(b1, qr[d0], p1, 0, 0, 0); }
; }
; template <int MODE, int SDEPTH, bool SIMPLE>
; __device__ __forceinline__ void attn_body(const Unit& U, char* lds, const int tid) {
;     ...
;   const int vb0 = (int)(uintptr_t)V_lds + v_rd_base(lane);
	v_mfma_f32_32x32x16_bf16 v[32:47], v[0:3], v[120:123], v[32:47]
	v_or_b32_e32 v0, 0x80, v192
	v_bitop3_b32 v0, v0, v8, v9 bitop3:0xde
	v_add_u32_e32 v206, 0, v0
	s_waitcnt lgkmcnt(0)
	v_mfma_f32_32x32x16_bf16 v[16:31], v[4:7], v[120:123], v[16:31]
	ds_read_b128 v[0:3], v206 offset:32768
	ds_read_b128 v[4:7], v206 offset:40960
	s_waitcnt vmcnt(3) lgkmcnt(1)
	v_mfma_f32_32x32x16_bf16 v[32:47], v[0:3], v[108:111], v[32:47]
	v_or_b32_e32 v0, 0xa0, v192
	v_bitop3_b32 v0, v0, v8, v9 bitop3:0xde
	v_add_u32_e32 v205, 0, v0
	ds_read_b128 v[0:3], v205 offset:32768
	s_waitcnt lgkmcnt(1)
	v_mfma_f32_32x32x16_bf16 v[16:31], v[4:7], v[108:111], v[16:31]
	v_and_b32_e32 v4, 0x3fffffc0, v52
	v_lshl_add_u32 v185, v4, 2, s22
	ds_read_b128 v[4:7], v205 offset:40960
	s_cselect_b32 s22, 0, 0
	v_lshl_add_u32 v186, v183, 2, v185
	s_waitcnt vmcnt(2) lgkmcnt(1)
	v_mfma_f32_32x32x16_bf16 v[32:47], v[0:3], v[104:107], v[32:47]
	v_and_b32_e32 v0, 0xc0, v53
	v_and_or_b32 v11, v10, 24, v0
	v_or_b32_e32 v0, 0xc0, v192
	v_bitop3_b32 v0, v0, v8, v9 bitop3:0xde
	v_add_u32_e32 v207, 0, v0
	ds_read_b128 v[0:3], v207 offset:32768
	s_waitcnt lgkmcnt(1)
	v_mfma_f32_32x32x16_bf16 v[16:31], v[4:7], v[104:107], v[16:31]
	v_and_b32_e32 v4, 32, v12
	v_and_b32_e32 v5, 0x100, v10
	v_or3_b32 v53, v11, v4, v5
	ds_read_b128 v[4:7], v207 offset:40960
	v_add_u32_e32 v189, s22, v53
	s_waitcnt vmcnt(1) lgkmcnt(1)
	v_mfma_f32_32x32x16_bf16 v[32:47], v[0:3], v[100:103], v[32:47]
	v_or_b32_e32 v0, 0xe0, v192
	v_bitop3_b32 v0, v0, v8, v9 bitop3:0xde
	v_add_u32_e32 v209, 0, v0
	ds_read_b128 v[0:3], v209 offset:32768
	ds_read_b128 v[54:57], v209 offset:40960
	s_waitcnt lgkmcnt(2)
	v_mfma_f32_32x32x16_bf16 v[16:31], v[4:7], v[100:103], v[16:31]
	s_waitcnt vmcnt(0) lgkmcnt(1)
	v_mfma_f32_32x32x16_bf16 v[32:47], v[0:3], v[96:99], v[32:47]
	v_mov_b64_e32 v[0:1], s[40:41]
	v_mov_b64_e32 v[2:3], s[42:43]
	v_mov_b64_e32 v[4:5], s[44:45]
	v_mov_b64_e32 v[6:7], s[46:47]
	v_mov_b64_e32 v[8:9], s[48:49]
	v_mov_b64_e32 v[10:11], s[50:51]
	v_mov_b64_e32 v[12:13], s[52:53]
	s_waitcnt lgkmcnt(0)
; #define SLOAD(i, k0) do { sr_[i].vs0 = *(const bf16x8*)(&Vh[(long)((k0) + sr) * LDK + sc]); sr_[i].vs1 = *(const bf16x8*)(&Vh[(long)((k0) + 32 + sr) * LDK + sc]); \
;     sr_[i].ks0 = *(const bf16x8*)(&Kh[(long)((k0) + sr) * LDK + sc]); sr_[i].ks1 = *(const bf16x8*)(&Kh[(long)((k0) + 32 + sr) * LDK + sc]); } while (0)
; #define SWRITE(b, i) do { *(bf16x8*)(V_lds + (b) * SHM_V + vst0) = sr_[i].vs0;          \
;     *(bf16x8*)(V_lds + (b) * SHM_V + vst1) = sr_[i].vs1; int kc = sc * 2;               \
;     *(bf16x8*)(K_lds + (b) * SHM_K + KSWZ(sr, kc)) = sr_[i].ks0;                       \
;     *(bf16x8*)(K_lds + (b) * SHM_K + KSWZ(32 + sr, kc)) = sr_[i].ks1; } while (0)
; #define SWAIT() do { if constexpr (SDEPTH == 2) asm volatile("s_waitcnt vmcnt(4)" ::: "memory"); else asm volatile("s_waitcnt vmcnt(0)" ::: "memory"); } while (0)
; __device__ __forceinline__ void partialSM(f32x16& p0, f32x16& p1, float& m_reg, float& mn, float& alpha) {
;   constexpr float C = SCALE * 1.4426950408889634f;
;   float pmax = p0[0];
; #pragma unroll
;   for (int r = 1; r < 16; ++r) pmax = fmaxf(pmax, p0[r]);
; #pragma unroll
;   for (int r = 0; r < 16; ++r) pmax = fmaxf(pmax, p1[r]);
;   { auto rr = __builtin_amdgcn_permlane32_swap(__float_as_uint(pmax), __float_as_uint(pmax), false, false);
;     pmax = fmaxf(__uint_as_float(rr[0]), __uint_as_float(rr[1])); }
;   if (__builtin_expect(__all(pmax - m_reg <= THR / SCALE), 1)) { mn = m_reg; alpha = 1.f; }
;   else { mn = fmaxf(m_reg, pmax); alpha = __builtin_amdgcn_exp2f((m_reg - mn) * C); m_reg = mn; }
;   float mnC = -mn * C;
; #pragma unroll
;   for (int r = 0; r < 16; ++r) p0[r] = fmaf(p0[r], C, mnC);
; #pragma unroll
;   for (int r = 0; r < 16; ++r) p1[r] = fmaf(p1[r], C, mnC);
; #pragma unroll
;   for (int r = 0; r < 16; ++r) p0[r] = __builtin_amdgcn_exp2f(p0[r]);
; }
; template <int MODE, int SDEPTH, bool SIMPLE>
; __device__ __forceinline__ void attn_body(const Unit& U, char* lds, const int tid) {
;     ...
;   SLOAD(SO, KVBLK); if constexpr (SDEPTH == 2) { if (2 < NT) SLOAD(SE, 2 * KVBLK); }
;   SWAIT(); SWRITE(1, SO); __syncthreads();
	v_mfma_f32_32x32x16_bf16 v[16:31], v[54:57], v[96:99], v[16:31]
	s_nop 2
	v_max_f32_e32 v54, v33, v33
	v_max_f32_e32 v55, v32, v32
	v_max_f32_e32 v54, v55, v54
	v_max3_f32 v54, v54, v34, v35
	v_max3_f32 v54, v54, v36, v37
	v_max3_f32 v54, v54, v38, v39
	v_max3_f32 v54, v54, v40, v41
	v_max3_f32 v54, v54, v42, v43
	v_max3_f32 v54, v54, v44, v45
	v_max3_f32 v54, v54, v46, v47
	v_max3_f32 v70, v54, v16, v17
	v_max3_f32 v70, v70, v18, v19
	v_max3_f32 v70, v70, v20, v21
	v_max3_f32 v70, v70, v22, v23
	v_max3_f32 v70, v70, v24, v25
	v_max3_f32 v70, v70, v26, v27
	v_mov_b64_e32 v[14:15], s[54:55]
	v_lshl_add_u64 v[54:55], s[2:3], 0, v[62:63]
	v_lshl_add_u64 v[62:63], s[0:1], 0, v[62:63]
	v_max3_f32 v70, v70, v28, v29
	s_mov_b64 s[44:45], 0x8000
	global_load_dwordx4 v[54:57], v[54:55], off
	s_nop 0
	global_load_dwordx4 v[58:61], v[58:59], off
	s_nop 0
	global_load_dwordx4 v[62:65], v[62:63], off
	s_nop 0
	global_load_dwordx4 v[66:69], v[66:67], off
	v_max3_f32 v76, v70, v30, v31
	v_lshl_add_u64 v[70:71], v[50:51], 0, s[44:45]
	v_lshl_add_u64 v[72:73], s[2:3], 0, v[70:71]
	v_lshl_add_u64 v[50:51], v[50:51], 0, s[26:27]
	v_lshl_add_u64 v[70:71], s[0:1], 0, v[70:71]
	v_lshl_add_u64 v[74:75], s[2:3], 0, v[50:51]
	global_load_dwordx4 v[128:131], v[72:73], off
	global_load_dwordx4 v[136:139], v[74:75], off
	v_lshl_add_u64 v[50:51], s[0:1], 0, v[50:51]
	global_load_dwordx4 v[132:135], v[70:71], off
	global_load_dwordx4 v[140:143], v[50:51], off
	v_mov_b32_e32 v77, v76
	s_nop 1
	v_permlane32_swap_b32_e32 v76, v77
	v_max_f32_e32 v50, v77, v77
	v_max_f32_e32 v51, v76, v76
	v_max_f32_e32 v50, v51, v50
	v_add_f32_e32 v51, 0x7149f2ca, v50
	v_max_f32_e32 v50, 0xf149f2ca, v50
	v_cmp_ge_f32_e32 vcc, s18, v51
	v_sub_f32_e32 v51, 0xf149f2ca, v50
	v_mul_f32_e32 v51, 0x3e0293ee, v51
	v_exp_f32_e32 v51, v51
	s_cmp_eq_u64 vcc, exec
	s_cselect_b64 vcc, -1, 0
	v_cndmask_b32_e32 v164, v50, v228, vcc
	v_mul_f32_e32 v50, 0xbe0293ee, v164
	s_or_b32 s0, s15, s21
	v_cndmask_b32_e64 v212, v51, 1.0, vcc
	v_mov_b32_e32 v51, v50
	s_ashr_i32 s1, s0, 31
	v_fmamk_f32 v32, v32, 0x3e0293ee, v50
	v_fmamk_f32 v33, v33, 0x3e0293ee, v50
	v_fmamk_f32 v34, v34, 0x3e0293ee, v50
	v_fmamk_f32 v35, v35, 0x3e0293ee, v50
	v_fmamk_f32 v36, v36, 0x3e0293ee, v50
	v_fmamk_f32 v37, v37, 0x3e0293ee, v50
	v_fmamk_f32 v38, v38, 0x3e0293ee, v50
	v_fmamk_f32 v39, v39, 0x3e0293ee, v50
	v_fmamk_f32 v40, v40, 0x3e0293ee, v50
	v_fmamk_f32 v41, v41, 0x3e0293ee, v50
	v_fmamk_f32 v42, v42, 0x3e0293ee, v50
	v_fmamk_f32 v43, v43, 0x3e0293ee, v50
	v_fmamk_f32 v44, v44, 0x3e0293ee, v50
	v_fmamk_f32 v45, v45, 0x3e0293ee, v50
	v_fmamk_f32 v46, v46, 0x3e0293ee, v50
	v_fmac_f32_e32 v51, 0x3e0293ee, v47
	s_lshl_b64 s[0:1], s[0:1], 21
	v_pk_fma_f32 v[154:155], v[18:19], s[12:13], v[50:51] op_sel_hi:[1,0,0]
	v_pk_fma_f32 v[156:157], v[16:17], s[12:13], v[50:51] op_sel_hi:[1,0,0]
	v_exp_f32_e32 v161, v32
	v_exp_f32_e32 v162, v33
	v_exp_f32_e32 v174, v34
	v_exp_f32_e32 v175, v35
	v_exp_f32_e32 v216, v36
	v_exp_f32_e32 v219, v37
	v_exp_f32_e32 v163, v38
	v_exp_f32_e32 v173, v39
	v_exp_f32_e32 v168, v40
	v_exp_f32_e32 v170, v41
	v_exp_f32_e32 v171, v42
	v_exp_f32_e32 v172, v43
	v_exp_f32_e32 v165, v44
	v_exp_f32_e32 v166, v45
	v_exp_f32_e32 v167, v46
	v_exp_f32_e32 v169, v51
	v_lshl_add_u64 v[16:17], s[0:1], 0, v[48:49]
	v_and_b32_e32 v18, 15, v52
	s_waitcnt vmcnt(4)
	s_addk_i32 s22, 0x4000
	v_lshl_or_b32 v16, v18, 4, v16
	v_pk_fma_f32 v[150:151], v[30:31], s[12:13], v[50:51] op_sel_hi:[1,0,0]
	v_pk_fma_f32 v[152:153], v[28:29], s[12:13], v[50:51] op_sel_hi:[1,0,0]
	v_pk_fma_f32 v[158:159], v[26:27], s[12:13], v[50:51] op_sel_hi:[1,0,0]
	v_pk_fma_f32 v[144:145], v[24:25], s[12:13], v[50:51] op_sel_hi:[1,0,0]
	v_pk_fma_f32 v[146:147], v[22:23], s[12:13], v[50:51] op_sel_hi:[1,0,0]
	v_pk_fma_f32 v[148:149], v[20:21], s[12:13], v[50:51] op_sel_hi:[1,0,0]
	s_waitcnt vmcnt(7)
	ds_write_b128 v191, v[54:57] offset:16384
	s_waitcnt vmcnt(6)
	ds_write_b128 v202, v[58:61] offset:16384
	s_waitcnt vmcnt(5)
	ds_write_b128 v190, v[62:65] offset:49152
	s_waitcnt vmcnt(4)
	ds_write_b128 v203, v[66:69] offset:49152
	v_add_u32_e32 v188, s22, v53
	v_lshl_add_u64 v[178:179], s[10:11], 0, v[16:17]
	s_nop 0
	v_readfirstlane_b32 s66, v178
	v_readfirstlane_b32 s67, v179
	s_nop 1
	v_subrev_u32_e32 v178, s66, v178
	s_sub_u32 s6, s66, 0x6000
	s_subb_u32 s7, s67, 0
	s_sub_u32 s4, s6, 0x800000
	s_subb_u32 s5, s7, 0
	v_add_u32_e32 v179, 0x2000, v178
	v_mov_b64_e32 v[62:63], v[14:15]
	v_mov_b64_e32 v[46:47], v[14:15]
	v_mov_b64_e32 v[30:31], v[14:15]
	v_mov_b64_e32 v[60:61], v[12:13]
	v_mov_b64_e32 v[58:59], v[10:11]
	v_mov_b64_e32 v[56:57], v[8:9]
	v_mov_b64_e32 v[54:55], v[6:7]
	v_mov_b64_e32 v[52:53], v[4:5]
	v_mov_b64_e32 v[50:51], v[2:3]
	v_mov_b64_e32 v[48:49], v[0:1]
	v_mov_b64_e32 v[44:45], v[12:13]
	v_mov_b64_e32 v[42:43], v[10:11]
	v_mov_b64_e32 v[40:41], v[8:9]
	v_mov_b64_e32 v[38:39], v[6:7]
	v_mov_b64_e32 v[36:37], v[4:5]
	v_mov_b64_e32 v[34:35], v[2:3]
	v_mov_b64_e32 v[32:33], v[0:1]
	v_mov_b64_e32 v[28:29], v[12:13]
	v_mov_b64_e32 v[26:27], v[10:11]
	v_mov_b64_e32 v[24:25], v[8:9]
	v_mov_b64_e32 v[22:23], v[6:7]
	v_mov_b64_e32 v[20:21], v[4:5]
	v_mov_b64_e32 v[18:19], v[2:3]
	v_mov_b64_e32 v[16:17], v[0:1]
	s_waitcnt lgkmcnt(0)
	s_barrier
	.p2align	6
